# v013 + MoBA unit: first q chunk for the gate scores is requested before the k_mean wait
# speedup vs baseline: 1.0027x; 1.0027x over previous
; __device__ __forceinline__ void moba_unit(const int wv, LAS unsigned char* lds, int b, int h, int qb, const bf16* Y, const float* kmean_l, bf16* OG) {
;     ...
;     const size_t rowblk = (size_t)b * T + 256 * qb;
;     { const float* src = kmean_l + (size_t)(b * NH + h) * 16 * 64; km[tid] = src[tid]; km[tid + 512] = src[tid + 512]; }
;     __syncthreads();
;     {
;         const int ql = tid >> 1, half = tid & 1;
;         const bf16* qrow = Y + (rowblk + ql) * MOBA_LDY + h * 64;
;         float g[8];
; #pragma unroll
;         for (int n = 0; n < 8; ++n) g[n] = 0.f;
; #pragma unroll 1
;         for (int c = 0; c < 8; ++c) {
;             const v4u qv = *(const v4u*)(qrow + 8 * c);
.LBB0_1156:
	s_lshl_b32 s0, s23, 1
	s_and_b32 s4, s0, 0x780
	s_lshl_b32 s0, s27, 1
	s_add_i32 s12, s3, s0
	s_bitcmp0_b32 s27, 0
	s_cselect_b32 s33, s22, s2
	s_ashr_i32 s8, s12, 4
	s_ashr_i32 s9, s8, 31
	s_lshl_b64 s[10:11], s[8:9], 12
	s_lshl_b32 s0, s33, 8
	s_ashr_i32 s13, s12, 31
	s_or_b32 s10, s10, s0
	s_lshl_b64 s[0:1], s[12:13], 12
	v_readlane_b32 s5, v254, 29
	v_mbcnt_lo_u32_b32 v12, -1, 0
	v_mbcnt_hi_u32_b32 v12, -1, v12
	s_add_u32 s0, s5, s0
	v_add_u32_e32 v0, s83, v12
	v_readlane_b32 s5, v254, 30
	s_addc_u32 s1, s5, s1
	v_ashrrev_i32_e32 v1, 31, v0
	v_lshl_add_u64 v[2:3], v[0:1], 2, s[0:1]
	global_load_dword v1, v[2:3], off
	v_lshl_add_u32 v4, v0, 2, 0
	global_load_dword v2, v[2:3], off offset:2048
	v_add_u32_e32 v4, 0x11000, v4
	v_ashrrev_i32_e32 v0, 1, v0
	v_readlane_b32 s0, v254, 27
	v_readlane_b32 s1, v254, 28
	s_add_u32 s0, s0, s4
	s_addc_u32 s1, s1, 0
	v_ashrrev_i32_e32 v61, 31, v0
	v_mov_b32_e32 v60, v0
	v_lshl_add_u64 v[60:61], s[10:11], 0, v[60:61]
	v_lshlrev_b64 v[60:61], 13, v[60:61]
	v_lshl_add_u64 v[60:61], s[0:1], 0, v[60:61]
	global_load_dwordx4 v[56:59], v[60:61], off
	v_mov_b32_e32 v10, 0
	v_mov_b32_e32 v11, v10
	v_mov_b32_e32 v8, v10
	v_mov_b32_e32 v9, v10
	v_mov_b32_e32 v5, v10
	s_waitcnt vmcnt(1)
	ds_write2st64_b32 v4, v1, v2 offset1:8
	v_ashrrev_i32_e32 v1, 31, v0
	v_lshl_add_u64 v[2:3], s[10:11], 0, v[0:1]
	v_lshlrev_b64 v[2:3], 13, v[2:3]
	v_and_b32_e32 v1, 1, v12
	v_lshl_add_u32 v13, v1, 11, 0
	v_lshl_add_u64 v[6:7], s[0:1], 0, v[2:3]
	s_mov_b32 s0, 0
	v_mov_b32_e32 v4, v10
	v_mov_b32_e32 v2, v10
	v_mov_b32_e32 v3, v10
	v_lshl_add_u64 v[6:7], v[6:7], 0, 16
	s_waitcnt lgkmcnt(0)
	s_barrier
